# dead B-address arithmetic in the s5_gemm loops replaced by s_nop after the LDS conversion
# baseline (speedup 1.0000x reference)
.LBB0_325:
	v_lshl_add_u64 v[158:159], v[78:79], 0, s[4:5]
	v_add_co_u32_e32 v130, vcc, s7, v158
	v_lshl_add_u64 v[162:163], v[80:81], 0, s[4:5]
	s_nop 0
	v_addc_co_u32_e32 v134, vcc, 0, v159, vcc
	v_add_co_u32_e32 v137, vcc, s7, v162
	s_nop 0
	s_nop 0
	v_addc_co_u32_e32 v158, vcc, 0, v163, vcc
	v_lshl_add_u64 v[162:163], v[82:83], 0, s[4:5]
	v_add_co_u32_e32 v159, vcc, s7, v162
	s_nop 0
	s_nop 0
	v_addc_co_u32_e32 v160, vcc, 0, v163, vcc
	v_lshl_add_u64 v[162:163], v[84:85], 0, s[4:5]
	v_add_co_u32_e32 v166, vcc, s7, v162
	s_nop 1
	v_addc_co_u32_e32 v168, vcc, 0, v163, vcc
	s_nop 0
	s_nop 0
	s_nop 0
	s_nop 0
	s_nop 0
	s_nop 0
	s_nop 0
	s_nop 0
	s_nop 0
	s_nop 0
	s_nop 0
	s_nop 0
	s_nop 0
	v_mov_b32_e32 v162, v130
	v_mov_b32_e32 v163, v134
	global_load_dwordx4 v[184:187], v[162:163], off offset:320
	v_mov_b32_e32 v162, v137
	v_mov_b32_e32 v163, v158
	global_load_dwordx4 v[188:191], v[162:163], off offset:320
	v_mov_b32_e32 v162, v159
	v_mov_b32_e32 v163, v160
	global_load_dwordx4 v[192:195], v[162:163], off offset:320
	v_mov_b32_e32 v158, v166
	v_mov_b32_e32 v159, v168
	global_load_dwordx4 v[212:215], v[158:159], off offset:320
	s_nop 0
	s_nop 0
	s_nop 0
	s_nop 0
	s_nop 0
	s_nop 0
	s_nop 0
	s_nop 0
	s_nop 0
	s_nop 0
	s_nop 0
	s_nop 0
	s_nop 0
	ds_read_b128 v[174:177], v222 offset:64
	s_nop 0
	s_nop 0
	ds_read_b128 v[168:171], v222 offset:16704
	s_nop 0
	s_nop 0
	ds_read_b128 v[180:183], v222 offset:33344
	s_nop 0
	s_nop 0
	ds_read_b128 v[218:221], v222 offset:49984
	v_lshl_add_u64 v[66:67], v[78:79], 0, s[4:5]
	v_add_co_u32_e32 v116, vcc, s7, v66
	v_lshl_add_u64 v[94:95], v[80:81], 0, s[4:5]
	s_nop 0
	v_addc_co_u32_e32 v117, vcc, 0, v67, vcc
	v_add_co_u32_e32 v114, vcc, s7, v94
	s_cmp_lt_u32 s3, 8
	s_nop 0
	v_addc_co_u32_e32 v115, vcc, 0, v95, vcc
	v_lshl_add_u64 v[94:95], v[82:83], 0, s[4:5]
	v_add_co_u32_e32 v98, vcc, s7, v94
	s_nop 0
	s_nop 0
	v_addc_co_u32_e32 v99, vcc, 0, v95, vcc
	v_lshl_add_u64 v[94:95], v[84:85], 0, s[4:5]
	v_add_co_u32_e32 v102, vcc, s7, v94
	s_nop 0
	s_nop 0
	v_addc_co_u32_e32 v103, vcc, 0, v95, vcc
	s_nop 0
	s_cselect_b64 vcc, -1, 0
	s_nop 0
	s_nop 0
	s_nop 0
	ds_read_b128 v[142:145], v222
	s_nop 0
	v_lshl_add_u64 v[104:105], v[88:89], 0, s[4:5]
	s_nop 0
	s_nop 0
	s_nop 0
	s_nop 0
	ds_read_b128 v[146:149], v222 offset:16640
	v_lshl_add_u64 v[106:107], v[72:73], 0, s[4:5]
	v_lshl_add_u64 v[110:111], v[90:91], 0, s[4:5]
	s_nop 0
	s_nop 0
	global_load_dwordx4 v[66:69], v[116:117], off offset:256
	global_load_dwordx4 v[120:123], v[114:115], off offset:256
	global_load_dwordx4 v[124:127], v[98:99], off offset:256
	s_nop 0
	s_nop 0
	ds_read_b128 v[150:153], v222 offset:33280
	s_nop 0
	s_nop 0
	s_nop 0
	s_nop 0
	s_nop 0
	s_nop 0
	ds_read_b128 v[154:157], v222 offset:49920
	global_load_dwordx4 v[138:141], v[102:103], off offset:256
	s_nop 0
	s_nop 0
	s_nop 0
	s_nop 0
	s_nop 0
	s_add_i32 s3, s3, 2
	s_add_u32 s4, s4, 0x80
	s_addc_u32 s5, s5, 0
	s_cmpk_lg_i32 s4, 0x400
	s_waitcnt vmcnt(0) lgkmcnt(0)
	v_mfma_f32_16x16x32_bf16 v[62:65], v[66:69], v[142:145], v[62:65]
	v_mfma_f32_16x16x32_bf16 v[58:61], v[66:69], v[146:149], v[58:61]
	s_waitcnt vmcnt(2)
	v_mfma_f32_16x16x32_bf16 v[54:57], v[66:69], v[150:153], v[54:57]
	s_waitcnt vmcnt(1)
	v_mfma_f32_16x16x32_bf16 v[50:53], v[66:69], v[154:157], v[50:53]
	v_mfma_f32_16x16x32_bf16 v[46:49], v[120:123], v[142:145], v[46:49]
	v_mfma_f32_16x16x32_bf16 v[42:45], v[120:123], v[146:149], v[42:45]
	v_mfma_f32_16x16x32_bf16 v[38:41], v[120:123], v[150:153], v[38:41]
	v_mfma_f32_16x16x32_bf16 v[34:37], v[120:123], v[154:157], v[34:37]
	v_mfma_f32_16x16x32_bf16 v[30:33], v[124:127], v[142:145], v[30:33]
	v_mfma_f32_16x16x32_bf16 v[26:29], v[124:127], v[146:149], v[26:29]
	v_mfma_f32_16x16x32_bf16 v[22:25], v[124:127], v[150:153], v[22:25]
	v_mfma_f32_16x16x32_bf16 v[18:21], v[124:127], v[154:157], v[18:21]
	s_nop 0
	s_nop 0
	s_nop 0
	v_lshl_add_u64 v[100:101], v[104:105], 0, s[16:17]
	v_lshl_add_u64 v[102:103], v[106:107], 0, s[10:11]
	v_lshl_add_u64 v[104:105], v[110:111], 0, s[16:17]
	s_nop 0
	s_nop 0
	s_nop 0
	v_cndmask_b32_e32 v103, v105, v103, vcc
	v_cndmask_b32_e32 v102, v104, v102, vcc
	s_nop 0
	s_nop 0
	s_waitcnt vmcnt(0)
	v_mfma_f32_16x16x32_bf16 v[14:17], v[138:141], v[142:145], v[14:17]
	s_nop 0
	v_mfma_f32_16x16x32_bf16 v[10:13], v[138:141], v[146:149], v[10:13]
	v_mfma_f32_16x16x32_bf16 v[6:9], v[138:141], v[150:153], v[6:9]
	v_mfma_f32_16x16x32_bf16 v[2:5], v[138:141], v[154:157], v[2:5]
	v_mfma_f32_16x16x32_bf16 v[62:65], v[184:187], v[174:177], v[62:65]
	v_mfma_f32_16x16x32_bf16 v[58:61], v[184:187], v[168:171], v[58:61]
	v_mfma_f32_16x16x32_bf16 v[54:57], v[184:187], v[180:183], v[54:57]
	v_mfma_f32_16x16x32_bf16 v[50:53], v[184:187], v[218:221], v[50:53]
	v_mfma_f32_16x16x32_bf16 v[46:49], v[188:191], v[174:177], v[46:49]
	v_mfma_f32_16x16x32_bf16 v[42:45], v[188:191], v[168:171], v[42:45]
	v_mfma_f32_16x16x32_bf16 v[38:41], v[188:191], v[180:183], v[38:41]
	v_mfma_f32_16x16x32_bf16 v[34:37], v[188:191], v[218:221], v[34:37]
	v_mfma_f32_16x16x32_bf16 v[30:33], v[192:195], v[174:177], v[30:33]
	v_mfma_f32_16x16x32_bf16 v[26:29], v[192:195], v[168:171], v[26:29]
	v_mfma_f32_16x16x32_bf16 v[22:25], v[192:195], v[180:183], v[22:25]
	v_mfma_f32_16x16x32_bf16 v[18:21], v[192:195], v[218:221], v[18:21]
	v_mfma_f32_16x16x32_bf16 v[14:17], v[212:215], v[174:177], v[14:17]
	v_mfma_f32_16x16x32_bf16 v[10:13], v[212:215], v[168:171], v[10:13]
	v_mfma_f32_16x16x32_bf16 v[6:9], v[212:215], v[180:183], v[6:9]
	v_mfma_f32_16x16x32_bf16 v[2:5], v[212:215], v[218:221], v[2:5]
	v_add_u32_e32 v222, 0x80, v222
	s_cbranch_scc1 .LBB0_325
	v_ashrrev_i32_e32 v1, 4, v1
	v_and_b32_e32 v68, -4, v1
	s_mov_b32 s3, s89
	v_ashrrev_i32_e32 v69, 31, v68
	v_lshl_add_u64 v[70:71], s[2:3], 0, v[68:69]
	v_mul_f32_e32 v69, 0x3d372713, v62
	v_mul_f32_e32 v69, v62, v69
	v_fma_f32 v69, v62, v69, v62
	v_mul_f32_e32 v69, 0x3f4c422a, v69
	v_mul_f32_e32 v69, -2.0, v69
	v_mul_f32_e32 v69, 0x3fb8aa3b, v69
	v_exp_f32_e32 v72, v69
	v_mul_f32_e32 v69, 0x3d372713, v63
	v_mul_f32_e32 v69, v63, v69
	v_fma_f32 v69, v63, v69, v63
	v_mul_f32_e32 v69, 0x3f4c422a, v69
	v_mul_f32_e32 v69, -2.0, v69
	v_mul_f32_e32 v69, 0x3fb8aa3b, v69
	v_exp_f32_e32 v73, v69
	v_lshlrev_b32_e32 v66, 3, v119
	v_readlane_b32 s0, v253, 57
	v_and_b32_e32 v130, 24, v66
	v_pk_add_f32 v[72:73], v[72:73], 1.0 op_sel_hi:[1,0]
	v_readlane_b32 s1, v253, 58
	v_div_scale_f32 v69, s[4:5], v73, v73, v63
	v_rcp_f32_e32 v74, v69
	v_lshl_add_u64 v[66:67], s[0:1], 0, v[130:131]
	v_or_b32_e32 v130, s6, v118
	v_fma_f32 v75, -v69, v74, 1.0
	v_fmac_f32_e32 v74, v75, v74
	v_div_scale_f32 v75, vcc, v63, v73, v63
	v_mul_f32_e32 v76, v75, v74
	v_fma_f32 v77, -v69, v76, v75
	v_fmac_f32_e32 v76, v77, v74
	v_fma_f32 v69, -v69, v76, v75
	v_div_fmas_f32 v69, v69, v74, v76
	v_div_fixup_f32 v63, v69, v73, v63
	v_div_scale_f32 v69, s[4:5], v72, v72, v62
	v_rcp_f32_e32 v73, v69
	s_barrier
	v_fma_f32 v74, -v69, v73, 1.0
	v_fmac_f32_e32 v73, v74, v73
	v_div_scale_f32 v74, vcc, v62, v72, v62
	v_mul_f32_e32 v75, v74, v73
	v_fma_f32 v76, -v69, v75, v74
	v_fmac_f32_e32 v75, v76, v73
	v_fma_f32 v69, -v69, v75, v74
	v_div_fmas_f32 v69, v69, v73, v75
	v_div_fixup_f32 v62, v69, v72, v62
	v_cvt_pk_bf16_f32 v62, v62, v63
	v_mul_f32_e32 v63, 0x3d372713, v64
	v_mul_f32_e32 v63, v64, v63
	v_fma_f32 v63, v64, v63, v64
	v_mul_f32_e32 v63, 0x3f4c422a, v63
	v_mul_f32_e32 v63, -2.0, v63
	v_mul_f32_e32 v63, 0x3fb8aa3b, v63
	v_exp_f32_e32 v72, v63
	v_mul_f32_e32 v63, 0x3d372713, v65
	v_mul_f32_e32 v63, v65, v63
	v_fma_f32 v63, v65, v63, v65
	v_mul_f32_e32 v63, 0x3f4c422a, v63
	v_mul_f32_e32 v63, -2.0, v63
	v_mul_f32_e32 v63, 0x3fb8aa3b, v63
	v_exp_f32_e32 v73, v63
	s_nop 0
	v_pk_add_f32 v[72:73], v[72:73], 1.0 op_sel_hi:[1,0]
	s_nop 0
	v_div_scale_f32 v63, s[4:5], v73, v73, v65
	v_rcp_f32_e32 v69, v63
	s_nop 0
	v_fma_f32 v74, -v63, v69, 1.0
	v_fmac_f32_e32 v69, v74, v69
	v_div_scale_f32 v74, vcc, v65, v73, v65
	v_mul_f32_e32 v75, v74, v69
	v_fma_f32 v76, -v63, v75, v74
	v_fmac_f32_e32 v75, v76, v69
	v_fma_f32 v63, -v63, v75, v74
	v_div_fmas_f32 v63, v63, v69, v75
	v_div_fixup_f32 v63, v63, v73, v65
	v_div_scale_f32 v65, s[4:5], v72, v72, v64
	v_rcp_f32_e32 v69, v65
	s_nop 0
	v_fma_f32 v73, -v65, v69, 1.0
	v_fmac_f32_e32 v69, v73, v69
	v_div_scale_f32 v73, vcc, v64, v72, v64
	v_mul_f32_e32 v74, v73, v69
	v_fma_f32 v75, -v65, v74, v73
	v_fmac_f32_e32 v74, v75, v69
	v_fma_f32 v65, -v65, v74, v73
	v_div_fmas_f32 v65, v65, v69, v74
	v_div_fixup_f32 v64, v65, v72, v64
	v_cvt_pk_bf16_f32 v63, v64, v63
	v_lshl_add_u64 v[64:65], v[70:71], 0, v[130:131]
	v_lshlrev_b64 v[64:65], 5, v[64:65]
	v_lshl_add_u64 v[64:65], v[66:67], 0, v[64:65]
	global_store_dwordx2 v[64:65], v[62:63], off
	v_mul_f32_e32 v62, 0x3d372713, v58
	v_mul_f32_e32 v63, 0x3d372713, v59
	v_mul_f32_e32 v62, v58, v62
	v_mul_f32_e32 v63, v59, v63
	v_fma_f32 v62, v58, v62, v58
	v_fma_f32 v63, v59, v63, v59
	v_mul_f32_e32 v62, 0x3f4c422a, v62
	v_mul_f32_e32 v63, 0x3f4c422a, v63
	v_mul_f32_e32 v62, -2.0, v62
	v_mul_f32_e32 v63, -2.0, v63
	v_mul_f32_e32 v62, 0x3fb8aa3b, v62
	v_mul_f32_e32 v63, 0x3fb8aa3b, v63
	v_exp_f32_e32 v62, v62
	v_exp_f32_e32 v63, v63
	s_nop 0
	v_pk_add_f32 v[62:63], v[62:63], 1.0 op_sel_hi:[1,0]
	s_nop 0
	v_div_scale_f32 v64, s[4:5], v63, v63, v59
	v_rcp_f32_e32 v65, v64
	s_nop 0
	v_fma_f32 v69, -v64, v65, 1.0
	v_fmac_f32_e32 v65, v69, v65
	v_div_scale_f32 v69, vcc, v59, v63, v59
	v_mul_f32_e32 v72, v69, v65
	v_fma_f32 v73, -v64, v72, v69
	v_fmac_f32_e32 v72, v73, v65
	v_fma_f32 v64, -v64, v72, v69
	v_div_fmas_f32 v64, v64, v65, v72
	v_div_fixup_f32 v59, v64, v63, v59
	v_div_scale_f32 v63, s[4:5], v62, v62, v58
	v_rcp_f32_e32 v64, v63
	s_nop 0
	v_fma_f32 v65, -v63, v64, 1.0
	v_fmac_f32_e32 v64, v65, v64
	v_div_scale_f32 v65, vcc, v58, v62, v58
	v_mul_f32_e32 v69, v65, v64
	v_fma_f32 v72, -v63, v69, v65
	v_fmac_f32_e32 v69, v72, v64
	v_fma_f32 v63, -v63, v69, v65
	v_div_fmas_f32 v63, v63, v64, v69
	v_div_fixup_f32 v58, v63, v62, v58
	v_cvt_pk_bf16_f32 v62, v58, v59
	v_mul_f32_e32 v58, 0x3d372713, v60
	v_mul_f32_e32 v59, 0x3d372713, v61
	v_mul_f32_e32 v58, v60, v58
	v_mul_f32_e32 v59, v61, v59
	v_fma_f32 v58, v60, v58, v60
	v_fma_f32 v59, v61, v59, v61
	v_mul_f32_e32 v58, 0x3f4c422a, v58
	v_mul_f32_e32 v59, 0x3f4c422a, v59
	v_mul_f32_e32 v58, -2.0, v58
	v_mul_f32_e32 v59, -2.0, v59
	v_mul_f32_e32 v58, 0x3fb8aa3b, v58
	v_mul_f32_e32 v59, 0x3fb8aa3b, v59
	v_exp_f32_e32 v58, v58
	v_exp_f32_e32 v59, v59
	s_nop 0
	v_pk_add_f32 v[58:59], v[58:59], 1.0 op_sel_hi:[1,0]
	s_nop 0
	v_div_scale_f32 v63, s[4:5], v59, v59, v61
	v_rcp_f32_e32 v64, v63
	s_nop 0
	v_fma_f32 v65, -v63, v64, 1.0
	v_fmac_f32_e32 v64, v65, v64
	v_div_scale_f32 v65, vcc, v61, v59, v61
	v_mul_f32_e32 v69, v65, v64
	v_fma_f32 v72, -v63, v69, v65
	v_fmac_f32_e32 v69, v72, v64
	v_fma_f32 v63, -v63, v69, v65
	v_div_fmas_f32 v63, v63, v64, v69
	v_div_fixup_f32 v59, v63, v59, v61
	v_div_scale_f32 v61, s[4:5], v58, v58, v60
	v_rcp_f32_e32 v63, v61
	s_nop 0
	v_fma_f32 v64, -v61, v63, 1.0
	v_fmac_f32_e32 v63, v64, v63
	v_div_scale_f32 v64, vcc, v60, v58, v60
	v_mul_f32_e32 v65, v64, v63
	v_fma_f32 v69, -v61, v65, v64
	v_fmac_f32_e32 v65, v69, v63
	v_fma_f32 v61, -v61, v65, v64
	v_div_fmas_f32 v61, v61, v63, v65
	v_div_fixup_f32 v58, v61, v58, v60
	v_cvt_pk_bf16_f32 v63, v58, v59
	v_or_b32_e32 v58, 0x100, v130
	v_mov_b32_e32 v59, v131
	v_lshl_add_u64 v[60:61], v[70:71], 0, v[58:59]
	v_lshlrev_b64 v[60:61], 5, v[60:61]
	v_lshl_add_u64 v[60:61], v[66:67], 0, v[60:61]
	global_store_dwordx2 v[60:61], v[62:63], off
	v_mul_f32_e32 v60, 0x3d372713, v54
	v_mul_f32_e32 v61, 0x3d372713, v55
	v_mul_f32_e32 v60, v54, v60
	v_mul_f32_e32 v61, v55, v61
	v_fma_f32 v60, v54, v60, v54
	v_fma_f32 v61, v55, v61, v55
	v_mul_f32_e32 v60, 0x3f4c422a, v60
	v_mul_f32_e32 v61, 0x3f4c422a, v61
	v_mul_f32_e32 v60, -2.0, v60
	v_mul_f32_e32 v61, -2.0, v61
	v_mul_f32_e32 v60, 0x3fb8aa3b, v60
	v_mul_f32_e32 v61, 0x3fb8aa3b, v61
	v_exp_f32_e32 v60, v60
	v_exp_f32_e32 v61, v61
	s_nop 0
	v_pk_add_f32 v[60:61], v[60:61], 1.0 op_sel_hi:[1,0]
	s_nop 0
	v_div_scale_f32 v62, s[4:5], v61, v61, v55
	v_rcp_f32_e32 v63, v62
	s_nop 0
	v_fma_f32 v64, -v62, v63, 1.0
	v_fmac_f32_e32 v63, v64, v63
	v_div_scale_f32 v64, vcc, v55, v61, v55
	v_mul_f32_e32 v65, v64, v63
	v_fma_f32 v69, -v62, v65, v64
	v_fmac_f32_e32 v65, v69, v63
	v_fma_f32 v62, -v62, v65, v64
	v_div_fmas_f32 v62, v62, v63, v65
	v_div_fixup_f32 v55, v62, v61, v55
	v_div_scale_f32 v61, s[4:5], v60, v60, v54
	v_rcp_f32_e32 v62, v61
	s_nop 0
	v_fma_f32 v63, -v61, v62, 1.0
	v_fmac_f32_e32 v62, v63, v62
	v_div_scale_f32 v63, vcc, v54, v60, v54
	v_mul_f32_e32 v64, v63, v62
	v_fma_f32 v65, -v61, v64, v63
	v_fmac_f32_e32 v64, v65, v62
	v_fma_f32 v61, -v61, v64, v63
	v_div_fmas_f32 v61, v61, v62, v64
	v_div_fixup_f32 v54, v61, v60, v54
	v_cvt_pk_bf16_f32 v60, v54, v55
	v_mul_f32_e32 v54, 0x3d372713, v56
	v_mul_f32_e32 v55, 0x3d372713, v57
	v_mul_f32_e32 v54, v56, v54
	v_mul_f32_e32 v55, v57, v55
	v_fma_f32 v54, v56, v54, v56
	v_fma_f32 v55, v57, v55, v57
	v_mul_f32_e32 v54, 0x3f4c422a, v54
	v_mul_f32_e32 v55, 0x3f4c422a, v55
	v_mul_f32_e32 v54, -2.0, v54
	v_mul_f32_e32 v55, -2.0, v55
	v_mul_f32_e32 v54, 0x3fb8aa3b, v54
	v_mul_f32_e32 v55, 0x3fb8aa3b, v55
	v_exp_f32_e32 v54, v54
	v_exp_f32_e32 v55, v55
	s_nop 0
	v_pk_add_f32 v[54:55], v[54:55], 1.0 op_sel_hi:[1,0]
	s_nop 0
	v_div_scale_f32 v61, s[4:5], v55, v55, v57
	v_rcp_f32_e32 v62, v61
	s_nop 0
	v_fma_f32 v63, -v61, v62, 1.0
	v_fmac_f32_e32 v62, v63, v62
	v_div_scale_f32 v63, vcc, v57, v55, v57
	v_mul_f32_e32 v64, v63, v62
	v_fma_f32 v65, -v61, v64, v63
	v_fmac_f32_e32 v64, v65, v62
	v_fma_f32 v61, -v61, v64, v63
	v_div_fmas_f32 v61, v61, v62, v64
	v_div_fixup_f32 v55, v61, v55, v57
	v_div_scale_f32 v57, s[4:5], v54, v54, v56
	v_rcp_f32_e32 v61, v57
	s_nop 0
	v_fma_f32 v62, -v57, v61, 1.0
	v_fmac_f32_e32 v61, v62, v61
	v_div_scale_f32 v62, vcc, v56, v54, v56
	v_mul_f32_e32 v63, v62, v61
	v_fma_f32 v64, -v57, v63, v62
	v_fmac_f32_e32 v63, v64, v61
	v_fma_f32 v57, -v57, v63, v62
	v_div_fmas_f32 v57, v57, v61, v63
	v_div_fixup_f32 v54, v57, v54, v56
	v_cvt_pk_bf16_f32 v61, v54, v55
	v_or_b32_e32 v54, 0x200, v130
	v_mov_b32_e32 v55, v131
	v_lshl_add_u64 v[56:57], v[70:71], 0, v[54:55]
	v_lshlrev_b64 v[56:57], 5, v[56:57]
	v_lshl_add_u64 v[56:57], v[66:67], 0, v[56:57]
	global_store_dwordx2 v[56:57], v[60:61], off
	v_mul_f32_e32 v56, 0x3d372713, v50
	v_mul_f32_e32 v57, 0x3d372713, v51
	v_mul_f32_e32 v56, v50, v56
	v_mul_f32_e32 v57, v51, v57
	v_fma_f32 v56, v50, v56, v50
	v_fma_f32 v57, v51, v57, v51
	v_mul_f32_e32 v56, 0x3f4c422a, v56
	v_mul_f32_e32 v57, 0x3f4c422a, v57
	v_mul_f32_e32 v56, -2.0, v56
	v_mul_f32_e32 v57, -2.0, v57
	v_mul_f32_e32 v56, 0x3fb8aa3b, v56
	v_mul_f32_e32 v57, 0x3fb8aa3b, v57
	v_exp_f32_e32 v56, v56
	v_exp_f32_e32 v57, v57
	s_nop 0
	v_pk_add_f32 v[56:57], v[56:57], 1.0 op_sel_hi:[1,0]
	s_nop 0
	v_div_scale_f32 v60, s[4:5], v57, v57, v51
	v_rcp_f32_e32 v61, v60
	s_nop 0
	v_fma_f32 v62, -v60, v61, 1.0
	v_fmac_f32_e32 v61, v62, v61
	v_div_scale_f32 v62, vcc, v51, v57, v51
	v_mul_f32_e32 v63, v62, v61
	v_fma_f32 v64, -v60, v63, v62
	v_fmac_f32_e32 v63, v64, v61
	v_fma_f32 v60, -v60, v63, v62
	v_div_fmas_f32 v60, v60, v61, v63
	v_div_fixup_f32 v51, v60, v57, v51
	v_div_scale_f32 v57, s[4:5], v56, v56, v50
	v_rcp_f32_e32 v60, v57
	s_nop 0
	v_fma_f32 v61, -v57, v60, 1.0
	v_fmac_f32_e32 v60, v61, v60
	v_div_scale_f32 v61, vcc, v50, v56, v50
	v_mul_f32_e32 v62, v61, v60
	v_fma_f32 v63, -v57, v62, v61
	v_fmac_f32_e32 v62, v63, v60
	v_fma_f32 v57, -v57, v62, v61
	v_div_fmas_f32 v57, v57, v60, v62
	v_div_fixup_f32 v50, v57, v56, v50
	v_cvt_pk_bf16_f32 v56, v50, v51
	v_mul_f32_e32 v50, 0x3d372713, v52
	v_mul_f32_e32 v51, 0x3d372713, v53
	v_mul_f32_e32 v50, v52, v50
	v_mul_f32_e32 v51, v53, v51
	v_fma_f32 v50, v52, v50, v52
	v_fma_f32 v51, v53, v51, v53
	v_mul_f32_e32 v50, 0x3f4c422a, v50
	v_mul_f32_e32 v51, 0x3f4c422a, v51
	v_mul_f32_e32 v50, -2.0, v50
	v_mul_f32_e32 v51, -2.0, v51
	v_mul_f32_e32 v50, 0x3fb8aa3b, v50
	v_mul_f32_e32 v51, 0x3fb8aa3b, v51
	v_exp_f32_e32 v50, v50
	v_exp_f32_e32 v51, v51
	s_nop 0
	v_pk_add_f32 v[50:51], v[50:51], 1.0 op_sel_hi:[1,0]
	s_nop 0
	v_div_scale_f32 v57, s[4:5], v51, v51, v53
	v_rcp_f32_e32 v60, v57
	s_nop 0
	v_fma_f32 v61, -v57, v60, 1.0
	v_fmac_f32_e32 v60, v61, v60
	v_div_scale_f32 v61, vcc, v53, v51, v53
	v_mul_f32_e32 v62, v61, v60
	v_fma_f32 v63, -v57, v62, v61
	v_fmac_f32_e32 v62, v63, v60
	v_fma_f32 v57, -v57, v62, v61
	v_div_fmas_f32 v57, v57, v60, v62
	v_div_fixup_f32 v51, v57, v51, v53
	v_div_scale_f32 v53, s[4:5], v50, v50, v52
	v_rcp_f32_e32 v57, v53
	s_nop 0
	v_fma_f32 v60, -v53, v57, 1.0
	v_fmac_f32_e32 v57, v60, v57
	v_div_scale_f32 v60, vcc, v52, v50, v52
	v_mul_f32_e32 v61, v60, v57
	v_fma_f32 v62, -v53, v61, v60
	v_fmac_f32_e32 v61, v62, v57
	v_fma_f32 v53, -v53, v61, v60
	v_div_fmas_f32 v53, v53, v57, v61
	v_div_fixup_f32 v50, v53, v50, v52
	v_cvt_pk_bf16_f32 v57, v50, v51
	v_or_b32_e32 v50, 0x300, v130
	v_mov_b32_e32 v51, v131
	v_lshl_add_u64 v[52:53], v[70:71], 0, v[50:51]
	v_lshlrev_b64 v[52:53], 5, v[52:53]
	v_lshl_add_u64 v[52:53], v[66:67], 0, v[52:53]
	global_store_dwordx2 v[52:53], v[56:57], off
	v_mul_f32_e32 v56, 0x3d372713, v46
	v_mul_f32_e32 v57, 0x3d372713, v47
	v_mul_f32_e32 v56, v46, v56
	v_mul_f32_e32 v57, v47, v57
	v_fma_f32 v56, v46, v56, v46
	v_fma_f32 v57, v47, v57, v47
	v_mul_f32_e32 v56, 0x3f4c422a, v56
	v_mul_f32_e32 v57, 0x3f4c422a, v57
	v_mul_f32_e32 v56, -2.0, v56
	v_mul_f32_e32 v57, -2.0, v57
	v_mul_f32_e32 v56, 0x3fb8aa3b, v56
	v_mul_f32_e32 v57, 0x3fb8aa3b, v57
	v_exp_f32_e32 v56, v56
	v_exp_f32_e32 v57, v57
	v_or_b32_e32 v52, 1, v68
	v_ashrrev_i32_e32 v53, 31, v52
	v_lshl_add_u64 v[52:53], s[2:3], 0, v[52:53]
	v_pk_add_f32 v[56:57], v[56:57], 1.0 op_sel_hi:[1,0]
	s_nop 0
	v_div_scale_f32 v60, s[4:5], v57, v57, v47
	v_rcp_f32_e32 v61, v60
	s_nop 0
	v_fma_f32 v62, -v60, v61, 1.0
	v_fmac_f32_e32 v61, v62, v61
	v_div_scale_f32 v62, vcc, v47, v57, v47
	v_mul_f32_e32 v63, v62, v61
	v_fma_f32 v64, -v60, v63, v62
	v_fmac_f32_e32 v63, v64, v61
	v_fma_f32 v60, -v60, v63, v62
	v_div_fmas_f32 v60, v60, v61, v63
	v_div_fixup_f32 v47, v60, v57, v47
	v_div_scale_f32 v57, s[4:5], v56, v56, v46
	v_rcp_f32_e32 v60, v57
	s_nop 0
	v_fma_f32 v61, -v57, v60, 1.0
	v_fmac_f32_e32 v60, v61, v60
	v_div_scale_f32 v61, vcc, v46, v56, v46
	v_mul_f32_e32 v62, v61, v60
	v_fma_f32 v63, -v57, v62, v61
	v_fmac_f32_e32 v62, v63, v60
	v_fma_f32 v57, -v57, v62, v61
	v_div_fmas_f32 v57, v57, v60, v62
	v_div_fixup_f32 v46, v57, v56, v46
	v_cvt_pk_bf16_f32 v46, v46, v47
	v_mul_f32_e32 v47, 0x3d372713, v48
	v_mul_f32_e32 v47, v48, v47
	v_fma_f32 v47, v48, v47, v48
	v_mul_f32_e32 v47, 0x3f4c422a, v47
	v_mul_f32_e32 v47, -2.0, v47
	v_mul_f32_e32 v47, 0x3fb8aa3b, v47
	v_exp_f32_e32 v56, v47
	v_mul_f32_e32 v47, 0x3d372713, v49
	v_mul_f32_e32 v47, v49, v47
	v_fma_f32 v47, v49, v47, v49
	v_mul_f32_e32 v47, 0x3f4c422a, v47
	v_mul_f32_e32 v47, -2.0, v47
	v_mul_f32_e32 v47, 0x3fb8aa3b, v47
	v_exp_f32_e32 v57, v47
	s_nop 0
	v_pk_add_f32 v[56:57], v[56:57], 1.0 op_sel_hi:[1,0]
	s_nop 0
	v_div_scale_f32 v47, s[4:5], v57, v57, v49
	v_rcp_f32_e32 v60, v47
	s_nop 0
	v_fma_f32 v61, -v47, v60, 1.0
	v_fmac_f32_e32 v60, v61, v60
	v_div_scale_f32 v61, vcc, v49, v57, v49
	v_mul_f32_e32 v62, v61, v60
	v_fma_f32 v63, -v47, v62, v61
	v_fmac_f32_e32 v62, v63, v60
	v_fma_f32 v47, -v47, v62, v61
	v_div_fmas_f32 v47, v47, v60, v62
	v_div_fixup_f32 v47, v47, v57, v49
	v_div_scale_f32 v49, s[4:5], v56, v56, v48
	v_rcp_f32_e32 v57, v49
	s_nop 0
	v_fma_f32 v60, -v49, v57, 1.0
	v_fmac_f32_e32 v57, v60, v57
	v_div_scale_f32 v60, vcc, v48, v56, v48
	v_mul_f32_e32 v61, v60, v57
	v_fma_f32 v62, -v49, v61, v60
	v_fmac_f32_e32 v61, v62, v57
	v_fma_f32 v49, -v49, v61, v60
	v_div_fmas_f32 v49, v49, v57, v61
	v_div_fixup_f32 v48, v49, v56, v48
	v_cvt_pk_bf16_f32 v47, v48, v47
	v_lshl_add_u64 v[48:49], v[52:53], 0, v[130:131]
	v_lshlrev_b64 v[48:49], 5, v[48:49]
	v_lshl_add_u64 v[48:49], v[66:67], 0, v[48:49]
	global_store_dwordx2 v[48:49], v[46:47], off
	v_mul_f32_e32 v46, 0x3d372713, v42
	v_mul_f32_e32 v47, 0x3d372713, v43
	v_mul_f32_e32 v46, v42, v46
	v_mul_f32_e32 v47, v43, v47
	v_fma_f32 v46, v42, v46, v42
	v_fma_f32 v47, v43, v47, v43
	v_mul_f32_e32 v46, 0x3f4c422a, v46
	v_mul_f32_e32 v47, 0x3f4c422a, v47
	v_mul_f32_e32 v46, -2.0, v46
	v_mul_f32_e32 v47, -2.0, v47
	v_mul_f32_e32 v46, 0x3fb8aa3b, v46
	v_mul_f32_e32 v47, 0x3fb8aa3b, v47
	v_exp_f32_e32 v46, v46
	v_exp_f32_e32 v47, v47
	s_nop 0
	v_pk_add_f32 v[46:47], v[46:47], 1.0 op_sel_hi:[1,0]
	s_nop 0
	v_div_scale_f32 v48, s[4:5], v47, v47, v43
	v_rcp_f32_e32 v49, v48
	s_nop 0
	v_fma_f32 v56, -v48, v49, 1.0
	v_fmac_f32_e32 v49, v56, v49
	v_div_scale_f32 v56, vcc, v43, v47, v43
	v_mul_f32_e32 v57, v56, v49
	v_fma_f32 v60, -v48, v57, v56
	v_fmac_f32_e32 v57, v60, v49
	v_fma_f32 v48, -v48, v57, v56
	v_div_fmas_f32 v48, v48, v49, v57
	v_div_fixup_f32 v43, v48, v47, v43
	v_div_scale_f32 v47, s[4:5], v46, v46, v42
	v_rcp_f32_e32 v48, v47
	s_nop 0
	v_fma_f32 v49, -v47, v48, 1.0
	v_fmac_f32_e32 v48, v49, v48
	v_div_scale_f32 v49, vcc, v42, v46, v42
	v_mul_f32_e32 v56, v49, v48
	v_fma_f32 v57, -v47, v56, v49
	v_fmac_f32_e32 v56, v57, v48
	v_fma_f32 v47, -v47, v56, v49
	v_div_fmas_f32 v47, v47, v48, v56
	v_div_fixup_f32 v42, v47, v46, v42
	v_cvt_pk_bf16_f32 v42, v42, v43
	v_mul_f32_e32 v43, 0x3d372713, v44
	v_mul_f32_e32 v43, v44, v43
	v_fma_f32 v43, v44, v43, v44
	v_mul_f32_e32 v43, 0x3f4c422a, v43
	v_mul_f32_e32 v43, -2.0, v43
	v_mul_f32_e32 v43, 0x3fb8aa3b, v43
	v_exp_f32_e32 v46, v43
	v_mul_f32_e32 v43, 0x3d372713, v45
	v_mul_f32_e32 v43, v45, v43
	v_fma_f32 v43, v45, v43, v45
	v_mul_f32_e32 v43, 0x3f4c422a, v43
	v_mul_f32_e32 v43, -2.0, v43
	v_mul_f32_e32 v43, 0x3fb8aa3b, v43
	v_exp_f32_e32 v47, v43
	s_nop 0
	v_pk_add_f32 v[46:47], v[46:47], 1.0 op_sel_hi:[1,0]
	s_nop 0
	v_div_scale_f32 v43, s[4:5], v47, v47, v45
	v_rcp_f32_e32 v48, v43
	s_nop 0
	v_fma_f32 v49, -v43, v48, 1.0
	v_fmac_f32_e32 v48, v49, v48
	v_div_scale_f32 v49, vcc, v45, v47, v45
	v_mul_f32_e32 v56, v49, v48
	v_fma_f32 v57, -v43, v56, v49
	v_fmac_f32_e32 v56, v57, v48
	v_fma_f32 v43, -v43, v56, v49
	v_div_fmas_f32 v43, v43, v48, v56
	v_div_fixup_f32 v43, v43, v47, v45
	v_div_scale_f32 v45, s[4:5], v46, v46, v44
	v_rcp_f32_e32 v47, v45
	s_nop 0
	v_fma_f32 v48, -v45, v47, 1.0
	v_fmac_f32_e32 v47, v48, v47
	v_div_scale_f32 v48, vcc, v44, v46, v44
	v_mul_f32_e32 v49, v48, v47
	v_fma_f32 v56, -v45, v49, v48
	v_fmac_f32_e32 v49, v56, v47
	v_fma_f32 v45, -v45, v49, v48
	v_div_fmas_f32 v45, v45, v47, v49
	v_div_fixup_f32 v44, v45, v46, v44
	v_cvt_pk_bf16_f32 v43, v44, v43
	v_lshl_add_u64 v[44:45], v[52:53], 0, v[58:59]
	v_lshlrev_b64 v[44:45], 5, v[44:45]
	v_lshl_add_u64 v[44:45], v[66:67], 0, v[44:45]
	global_store_dwordx2 v[44:45], v[42:43], off
	v_mul_f32_e32 v42, 0x3d372713, v38
	v_mul_f32_e32 v43, 0x3d372713, v39
	v_mul_f32_e32 v42, v38, v42
	v_mul_f32_e32 v43, v39, v43
	v_fma_f32 v42, v38, v42, v38
	v_fma_f32 v43, v39, v43, v39
	v_mul_f32_e32 v42, 0x3f4c422a, v42
	v_mul_f32_e32 v43, 0x3f4c422a, v43
	v_mul_f32_e32 v42, -2.0, v42
	v_mul_f32_e32 v43, -2.0, v43
	v_mul_f32_e32 v42, 0x3fb8aa3b, v42
	v_mul_f32_e32 v43, 0x3fb8aa3b, v43
	v_exp_f32_e32 v42, v42
	v_exp_f32_e32 v43, v43
	s_nop 0
	v_pk_add_f32 v[42:43], v[42:43], 1.0 op_sel_hi:[1,0]
	s_nop 0
	v_div_scale_f32 v44, s[4:5], v43, v43, v39
	v_rcp_f32_e32 v45, v44
	s_nop 0
	v_fma_f32 v46, -v44, v45, 1.0
	v_fmac_f32_e32 v45, v46, v45
	v_div_scale_f32 v46, vcc, v39, v43, v39
	v_mul_f32_e32 v47, v46, v45
	v_fma_f32 v48, -v44, v47, v46
	v_fmac_f32_e32 v47, v48, v45
	v_fma_f32 v44, -v44, v47, v46
	v_div_fmas_f32 v44, v44, v45, v47
	v_div_fixup_f32 v39, v44, v43, v39
	v_div_scale_f32 v43, s[4:5], v42, v42, v38
	v_rcp_f32_e32 v44, v43
	s_nop 0
	v_fma_f32 v45, -v43, v44, 1.0
	v_fmac_f32_e32 v44, v45, v44
	v_div_scale_f32 v45, vcc, v38, v42, v38
	v_mul_f32_e32 v46, v45, v44
	v_fma_f32 v47, -v43, v46, v45
	v_fmac_f32_e32 v46, v47, v44
	v_fma_f32 v43, -v43, v46, v45
	v_div_fmas_f32 v43, v43, v44, v46
	v_div_fixup_f32 v38, v43, v42, v38
	v_cvt_pk_bf16_f32 v38, v38, v39
	v_mul_f32_e32 v39, 0x3d372713, v40
	v_mul_f32_e32 v39, v40, v39
	v_fma_f32 v39, v40, v39, v40
	v_mul_f32_e32 v39, 0x3f4c422a, v39
	v_mul_f32_e32 v39, -2.0, v39
	v_mul_f32_e32 v39, 0x3fb8aa3b, v39
	v_exp_f32_e32 v42, v39
	v_mul_f32_e32 v39, 0x3d372713, v41
	v_mul_f32_e32 v39, v41, v39
	v_fma_f32 v39, v41, v39, v41
	v_mul_f32_e32 v39, 0x3f4c422a, v39
	v_mul_f32_e32 v39, -2.0, v39
	v_mul_f32_e32 v39, 0x3fb8aa3b, v39
	v_exp_f32_e32 v43, v39
	s_nop 0
	v_pk_add_f32 v[42:43], v[42:43], 1.0 op_sel_hi:[1,0]
	s_nop 0
	v_div_scale_f32 v39, s[4:5], v43, v43, v41
	v_rcp_f32_e32 v44, v39
	s_nop 0
	v_fma_f32 v45, -v39, v44, 1.0
	v_fmac_f32_e32 v44, v45, v44
	v_div_scale_f32 v45, vcc, v41, v43, v41
	v_mul_f32_e32 v46, v45, v44
	v_fma_f32 v47, -v39, v46, v45
	v_fmac_f32_e32 v46, v47, v44
	v_fma_f32 v39, -v39, v46, v45
	v_div_fmas_f32 v39, v39, v44, v46
	v_div_fixup_f32 v39, v39, v43, v41
	v_div_scale_f32 v41, s[4:5], v42, v42, v40
	v_rcp_f32_e32 v43, v41
	s_nop 0
	v_fma_f32 v44, -v41, v43, 1.0
	v_fmac_f32_e32 v43, v44, v43
	v_div_scale_f32 v44, vcc, v40, v42, v40
	v_mul_f32_e32 v45, v44, v43
	v_fma_f32 v46, -v41, v45, v44
	v_fmac_f32_e32 v45, v46, v43
	v_fma_f32 v41, -v41, v45, v44
	v_div_fmas_f32 v41, v41, v43, v45
	v_div_fixup_f32 v40, v41, v42, v40
	v_cvt_pk_bf16_f32 v39, v40, v39
	v_lshl_add_u64 v[40:41], v[52:53], 0, v[54:55]
	v_lshlrev_b64 v[40:41], 5, v[40:41]
	v_lshl_add_u64 v[40:41], v[66:67], 0, v[40:41]
	global_store_dwordx2 v[40:41], v[38:39], off
	v_mul_f32_e32 v38, 0x3d372713, v34
	v_mul_f32_e32 v39, 0x3d372713, v35
	v_mul_f32_e32 v38, v34, v38
	v_mul_f32_e32 v39, v35, v39
	v_fma_f32 v38, v34, v38, v34
	v_fma_f32 v39, v35, v39, v35
	v_mul_f32_e32 v38, 0x3f4c422a, v38
	v_mul_f32_e32 v39, 0x3f4c422a, v39
	v_mul_f32_e32 v38, -2.0, v38
	v_mul_f32_e32 v39, -2.0, v39
	v_mul_f32_e32 v38, 0x3fb8aa3b, v38
	v_mul_f32_e32 v39, 0x3fb8aa3b, v39
	v_exp_f32_e32 v38, v38
	v_exp_f32_e32 v39, v39
	s_nop 0
	v_pk_add_f32 v[38:39], v[38:39], 1.0 op_sel_hi:[1,0]
	s_nop 0
	v_div_scale_f32 v40, s[4:5], v39, v39, v35
	v_rcp_f32_e32 v41, v40
	s_nop 0
	v_fma_f32 v42, -v40, v41, 1.0
	v_fmac_f32_e32 v41, v42, v41
	v_div_scale_f32 v42, vcc, v35, v39, v35
	v_mul_f32_e32 v43, v42, v41
	v_fma_f32 v44, -v40, v43, v42
	v_fmac_f32_e32 v43, v44, v41
	v_fma_f32 v40, -v40, v43, v42
	v_div_fmas_f32 v40, v40, v41, v43
	v_div_fixup_f32 v35, v40, v39, v35
	v_div_scale_f32 v39, s[4:5], v38, v38, v34
	v_rcp_f32_e32 v40, v39
	s_nop 0
	v_fma_f32 v41, -v39, v40, 1.0
	v_fmac_f32_e32 v40, v41, v40
	v_div_scale_f32 v41, vcc, v34, v38, v34
	v_mul_f32_e32 v42, v41, v40
	v_fma_f32 v43, -v39, v42, v41
	v_fmac_f32_e32 v42, v43, v40
	v_fma_f32 v39, -v39, v42, v41
	v_div_fmas_f32 v39, v39, v40, v42
	v_div_fixup_f32 v34, v39, v38, v34
	v_cvt_pk_bf16_f32 v34, v34, v35
	v_mul_f32_e32 v35, 0x3d372713, v36
	v_mul_f32_e32 v35, v36, v35
	v_fma_f32 v35, v36, v35, v36
	v_mul_f32_e32 v35, 0x3f4c422a, v35
	v_mul_f32_e32 v35, -2.0, v35
	v_mul_f32_e32 v35, 0x3fb8aa3b, v35
	v_exp_f32_e32 v38, v35
	v_mul_f32_e32 v35, 0x3d372713, v37
	v_mul_f32_e32 v35, v37, v35
	v_fma_f32 v35, v37, v35, v37
	v_mul_f32_e32 v35, 0x3f4c422a, v35
	v_mul_f32_e32 v35, -2.0, v35
	v_mul_f32_e32 v35, 0x3fb8aa3b, v35
	v_exp_f32_e32 v39, v35
	s_nop 0
	v_pk_add_f32 v[38:39], v[38:39], 1.0 op_sel_hi:[1,0]
	s_nop 0
	v_div_scale_f32 v35, s[4:5], v39, v39, v37
	v_rcp_f32_e32 v40, v35
	s_nop 0
	v_fma_f32 v41, -v35, v40, 1.0
	v_fmac_f32_e32 v40, v41, v40
	v_div_scale_f32 v41, vcc, v37, v39, v37
	v_mul_f32_e32 v42, v41, v40
	v_fma_f32 v43, -v35, v42, v41
	v_fmac_f32_e32 v42, v43, v40
	v_fma_f32 v35, -v35, v42, v41
	v_div_fmas_f32 v35, v35, v40, v42
	v_div_fixup_f32 v35, v35, v39, v37
	v_div_scale_f32 v37, s[4:5], v38, v38, v36
	v_rcp_f32_e32 v39, v37
	s_nop 0
	v_fma_f32 v40, -v37, v39, 1.0
	v_fmac_f32_e32 v39, v40, v39
	v_div_scale_f32 v40, vcc, v36, v38, v36
	v_mul_f32_e32 v41, v40, v39
	v_fma_f32 v42, -v37, v41, v40
	v_fmac_f32_e32 v41, v42, v39
	v_fma_f32 v37, -v37, v41, v40
	v_div_fmas_f32 v37, v37, v39, v41
	v_div_fixup_f32 v36, v37, v38, v36
	v_cvt_pk_bf16_f32 v35, v36, v35
	v_lshl_add_u64 v[36:37], v[52:53], 0, v[50:51]
	v_lshlrev_b64 v[36:37], 5, v[36:37]
	v_lshl_add_u64 v[36:37], v[66:67], 0, v[36:37]
	global_store_dwordx2 v[36:37], v[34:35], off
	v_mul_f32_e32 v36, 0x3d372713, v30
	v_mul_f32_e32 v37, 0x3d372713, v31
	v_mul_f32_e32 v36, v30, v36
	v_mul_f32_e32 v37, v31, v37
	v_fma_f32 v36, v30, v36, v30
	v_fma_f32 v37, v31, v37, v31
	v_mul_f32_e32 v36, 0x3f4c422a, v36
	v_mul_f32_e32 v37, 0x3f4c422a, v37
	v_mul_f32_e32 v36, -2.0, v36
	v_mul_f32_e32 v37, -2.0, v37
	v_mul_f32_e32 v36, 0x3fb8aa3b, v36
	v_mul_f32_e32 v37, 0x3fb8aa3b, v37
	v_exp_f32_e32 v36, v36
	v_exp_f32_e32 v37, v37
	v_or_b32_e32 v34, 2, v68
	v_ashrrev_i32_e32 v35, 31, v34
	v_lshl_add_u64 v[34:35], s[2:3], 0, v[34:35]
	v_pk_add_f32 v[36:37], v[36:37], 1.0 op_sel_hi:[1,0]
	s_nop 0
	v_div_scale_f32 v38, s[4:5], v37, v37, v31
	v_rcp_f32_e32 v39, v38
	s_nop 0
	v_fma_f32 v40, -v38, v39, 1.0
	v_fmac_f32_e32 v39, v40, v39
	v_div_scale_f32 v40, vcc, v31, v37, v31
	v_mul_f32_e32 v41, v40, v39
	v_fma_f32 v42, -v38, v41, v40
	v_fmac_f32_e32 v41, v42, v39
	v_fma_f32 v38, -v38, v41, v40
	v_div_fmas_f32 v38, v38, v39, v41
	v_div_fixup_f32 v31, v38, v37, v31
	v_div_scale_f32 v37, s[4:5], v36, v36, v30
	v_rcp_f32_e32 v38, v37
	s_nop 0
	v_fma_f32 v39, -v37, v38, 1.0
	v_fmac_f32_e32 v38, v39, v38
	v_div_scale_f32 v39, vcc, v30, v36, v30
	v_mul_f32_e32 v40, v39, v38
	v_fma_f32 v41, -v37, v40, v39
	v_fmac_f32_e32 v40, v41, v38
	v_fma_f32 v37, -v37, v40, v39
	v_div_fmas_f32 v37, v37, v38, v40
	v_div_fixup_f32 v30, v37, v36, v30
	v_cvt_pk_bf16_f32 v30, v30, v31
	v_mul_f32_e32 v31, 0x3d372713, v32
	v_mul_f32_e32 v31, v32, v31
	v_fma_f32 v31, v32, v31, v32
	v_mul_f32_e32 v31, 0x3f4c422a, v31
	v_mul_f32_e32 v31, -2.0, v31
	v_mul_f32_e32 v31, 0x3fb8aa3b, v31
	v_exp_f32_e32 v36, v31
	v_mul_f32_e32 v31, 0x3d372713, v33
	v_mul_f32_e32 v31, v33, v31
	v_fma_f32 v31, v33, v31, v33
	v_mul_f32_e32 v31, 0x3f4c422a, v31
	v_mul_f32_e32 v31, -2.0, v31
	v_mul_f32_e32 v31, 0x3fb8aa3b, v31
	v_exp_f32_e32 v37, v31
	s_nop 0
	v_pk_add_f32 v[36:37], v[36:37], 1.0 op_sel_hi:[1,0]
	s_nop 0
	v_div_scale_f32 v31, s[4:5], v37, v37, v33
	v_rcp_f32_e32 v38, v31
	s_nop 0
	v_fma_f32 v39, -v31, v38, 1.0
	v_fmac_f32_e32 v38, v39, v38
	v_div_scale_f32 v39, vcc, v33, v37, v33
	v_mul_f32_e32 v40, v39, v38
	v_fma_f32 v41, -v31, v40, v39
	v_fmac_f32_e32 v40, v41, v38
	v_fma_f32 v31, -v31, v40, v39
	v_div_fmas_f32 v31, v31, v38, v40
	v_div_fixup_f32 v31, v31, v37, v33
	v_div_scale_f32 v33, s[4:5], v36, v36, v32
	v_rcp_f32_e32 v37, v33
	s_nop 0
	v_fma_f32 v38, -v33, v37, 1.0
	v_fmac_f32_e32 v37, v38, v37
	v_div_scale_f32 v38, vcc, v32, v36, v32
	v_mul_f32_e32 v39, v38, v37
	v_fma_f32 v40, -v33, v39, v38
	v_fmac_f32_e32 v39, v40, v37
	v_fma_f32 v33, -v33, v39, v38
	v_div_fmas_f32 v33, v33, v37, v39
	v_div_fixup_f32 v32, v33, v36, v32
	v_cvt_pk_bf16_f32 v31, v32, v31
	v_lshl_add_u64 v[32:33], v[34:35], 0, v[130:131]
	v_lshlrev_b64 v[32:33], 5, v[32:33]
	v_lshl_add_u64 v[32:33], v[66:67], 0, v[32:33]
	global_store_dwordx2 v[32:33], v[30:31], off
	v_mul_f32_e32 v30, 0x3d372713, v26
	v_mul_f32_e32 v31, 0x3d372713, v27
	v_mul_f32_e32 v30, v26, v30
	v_mul_f32_e32 v31, v27, v31
	v_fma_f32 v30, v26, v30, v26
	v_fma_f32 v31, v27, v31, v27
	v_mul_f32_e32 v30, 0x3f4c422a, v30
	v_mul_f32_e32 v31, 0x3f4c422a, v31
	v_mul_f32_e32 v30, -2.0, v30
	v_mul_f32_e32 v31, -2.0, v31
	v_mul_f32_e32 v30, 0x3fb8aa3b, v30
	v_mul_f32_e32 v31, 0x3fb8aa3b, v31
	v_exp_f32_e32 v30, v30
	v_exp_f32_e32 v31, v31
	s_nop 0
	v_pk_add_f32 v[30:31], v[30:31], 1.0 op_sel_hi:[1,0]
	s_nop 0
	v_div_scale_f32 v32, s[4:5], v31, v31, v27
	v_rcp_f32_e32 v33, v32
	s_nop 0
	v_fma_f32 v36, -v32, v33, 1.0
	v_fmac_f32_e32 v33, v36, v33
	v_div_scale_f32 v36, vcc, v27, v31, v27
	v_mul_f32_e32 v37, v36, v33
	v_fma_f32 v38, -v32, v37, v36
	v_fmac_f32_e32 v37, v38, v33
	v_fma_f32 v32, -v32, v37, v36
	v_div_fmas_f32 v32, v32, v33, v37
	v_div_fixup_f32 v27, v32, v31, v27
	v_div_scale_f32 v31, s[4:5], v30, v30, v26
	v_rcp_f32_e32 v32, v31
	s_nop 0
	v_fma_f32 v33, -v31, v32, 1.0
	v_fmac_f32_e32 v32, v33, v32
	v_div_scale_f32 v33, vcc, v26, v30, v26
	v_mul_f32_e32 v36, v33, v32
	v_fma_f32 v37, -v31, v36, v33
	v_fmac_f32_e32 v36, v37, v32
	v_fma_f32 v31, -v31, v36, v33
	v_div_fmas_f32 v31, v31, v32, v36
	v_div_fixup_f32 v26, v31, v30, v26
	v_cvt_pk_bf16_f32 v26, v26, v27
	v_mul_f32_e32 v27, 0x3d372713, v28
	v_mul_f32_e32 v27, v28, v27
	v_fma_f32 v27, v28, v27, v28
	v_mul_f32_e32 v27, 0x3f4c422a, v27
	v_mul_f32_e32 v27, -2.0, v27
	v_mul_f32_e32 v27, 0x3fb8aa3b, v27
	v_exp_f32_e32 v30, v27
	v_mul_f32_e32 v27, 0x3d372713, v29
	v_mul_f32_e32 v27, v29, v27
	v_fma_f32 v27, v29, v27, v29
	v_mul_f32_e32 v27, 0x3f4c422a, v27
	v_mul_f32_e32 v27, -2.0, v27
	v_mul_f32_e32 v27, 0x3fb8aa3b, v27
	v_exp_f32_e32 v31, v27
	s_nop 0
	v_pk_add_f32 v[30:31], v[30:31], 1.0 op_sel_hi:[1,0]
	s_nop 0
	v_div_scale_f32 v27, s[4:5], v31, v31, v29
	v_rcp_f32_e32 v32, v27
	s_nop 0
	v_fma_f32 v33, -v27, v32, 1.0
	v_fmac_f32_e32 v32, v33, v32
	v_div_scale_f32 v33, vcc, v29, v31, v29
	v_mul_f32_e32 v36, v33, v32
	v_fma_f32 v37, -v27, v36, v33
	v_fmac_f32_e32 v36, v37, v32
	v_fma_f32 v27, -v27, v36, v33
	v_div_fmas_f32 v27, v27, v32, v36
	v_div_fixup_f32 v27, v27, v31, v29
	v_div_scale_f32 v29, s[4:5], v30, v30, v28
	v_rcp_f32_e32 v31, v29
	s_nop 0
	v_fma_f32 v32, -v29, v31, 1.0
	v_fmac_f32_e32 v31, v32, v31
	v_div_scale_f32 v32, vcc, v28, v30, v28
	v_mul_f32_e32 v33, v32, v31
	v_fma_f32 v36, -v29, v33, v32
	v_fmac_f32_e32 v33, v36, v31
	v_fma_f32 v29, -v29, v33, v32
	v_div_fmas_f32 v29, v29, v31, v33
	v_div_fixup_f32 v28, v29, v30, v28
	v_cvt_pk_bf16_f32 v27, v28, v27
	v_lshl_add_u64 v[28:29], v[34:35], 0, v[58:59]
	v_lshlrev_b64 v[28:29], 5, v[28:29]
	v_lshl_add_u64 v[28:29], v[66:67], 0, v[28:29]
	global_store_dwordx2 v[28:29], v[26:27], off
	v_mul_f32_e32 v26, 0x3d372713, v22
	v_mul_f32_e32 v27, 0x3d372713, v23
	v_mul_f32_e32 v26, v22, v26
	v_mul_f32_e32 v27, v23, v27
	v_fma_f32 v26, v22, v26, v22
	v_fma_f32 v27, v23, v27, v23
	v_mul_f32_e32 v26, 0x3f4c422a, v26
	v_mul_f32_e32 v27, 0x3f4c422a, v27
	v_mul_f32_e32 v26, -2.0, v26
	v_mul_f32_e32 v27, -2.0, v27
	v_mul_f32_e32 v26, 0x3fb8aa3b, v26
	v_mul_f32_e32 v27, 0x3fb8aa3b, v27
	v_exp_f32_e32 v26, v26
	v_exp_f32_e32 v27, v27
	s_nop 0
	v_pk_add_f32 v[26:27], v[26:27], 1.0 op_sel_hi:[1,0]
	s_nop 0
	v_div_scale_f32 v28, s[4:5], v27, v27, v23
	v_rcp_f32_e32 v29, v28
	s_nop 0
	v_fma_f32 v30, -v28, v29, 1.0
	v_fmac_f32_e32 v29, v30, v29
	v_div_scale_f32 v30, vcc, v23, v27, v23
	v_mul_f32_e32 v31, v30, v29
	v_fma_f32 v32, -v28, v31, v30
	v_fmac_f32_e32 v31, v32, v29
	v_fma_f32 v28, -v28, v31, v30
	v_div_fmas_f32 v28, v28, v29, v31
	v_div_fixup_f32 v23, v28, v27, v23
	v_div_scale_f32 v27, s[4:5], v26, v26, v22
	v_rcp_f32_e32 v28, v27
	s_nop 0
	v_fma_f32 v29, -v27, v28, 1.0
	v_fmac_f32_e32 v28, v29, v28
	v_div_scale_f32 v29, vcc, v22, v26, v22
	v_mul_f32_e32 v30, v29, v28
	v_fma_f32 v31, -v27, v30, v29
	v_fmac_f32_e32 v30, v31, v28
	v_fma_f32 v27, -v27, v30, v29
	v_div_fmas_f32 v27, v27, v28, v30
	v_div_fixup_f32 v22, v27, v26, v22
	v_cvt_pk_bf16_f32 v22, v22, v23
	v_mul_f32_e32 v23, 0x3d372713, v24
	v_mul_f32_e32 v23, v24, v23
	v_fma_f32 v23, v24, v23, v24
	v_mul_f32_e32 v23, 0x3f4c422a, v23
	v_mul_f32_e32 v23, -2.0, v23
	v_mul_f32_e32 v23, 0x3fb8aa3b, v23
	v_exp_f32_e32 v26, v23
	v_mul_f32_e32 v23, 0x3d372713, v25
	v_mul_f32_e32 v23, v25, v23
	v_fma_f32 v23, v25, v23, v25
	v_mul_f32_e32 v23, 0x3f4c422a, v23
	v_mul_f32_e32 v23, -2.0, v23
	v_mul_f32_e32 v23, 0x3fb8aa3b, v23
	v_exp_f32_e32 v27, v23
	s_nop 0
	v_pk_add_f32 v[26:27], v[26:27], 1.0 op_sel_hi:[1,0]
	s_nop 0
	v_div_scale_f32 v23, s[4:5], v27, v27, v25
	v_rcp_f32_e32 v28, v23
	s_nop 0
	v_fma_f32 v29, -v23, v28, 1.0
	v_fmac_f32_e32 v28, v29, v28
	v_div_scale_f32 v29, vcc, v25, v27, v25
	v_mul_f32_e32 v30, v29, v28
	v_fma_f32 v31, -v23, v30, v29
	v_fmac_f32_e32 v30, v31, v28
	v_fma_f32 v23, -v23, v30, v29
	v_div_fmas_f32 v23, v23, v28, v30
	v_div_fixup_f32 v23, v23, v27, v25
	v_div_scale_f32 v25, s[4:5], v26, v26, v24
	v_rcp_f32_e32 v27, v25
	s_nop 0
	v_fma_f32 v28, -v25, v27, 1.0
	v_fmac_f32_e32 v27, v28, v27
	v_div_scale_f32 v28, vcc, v24, v26, v24
	v_mul_f32_e32 v29, v28, v27
	v_fma_f32 v30, -v25, v29, v28
	v_fmac_f32_e32 v29, v30, v27
	v_fma_f32 v25, -v25, v29, v28
	v_div_fmas_f32 v25, v25, v27, v29
	v_div_fixup_f32 v24, v25, v26, v24
	v_cvt_pk_bf16_f32 v23, v24, v23
	v_lshl_add_u64 v[24:25], v[34:35], 0, v[54:55]
	v_lshlrev_b64 v[24:25], 5, v[24:25]
	v_lshl_add_u64 v[24:25], v[66:67], 0, v[24:25]
	global_store_dwordx2 v[24:25], v[22:23], off
	v_mul_f32_e32 v22, 0x3d372713, v18
	v_mul_f32_e32 v23, 0x3d372713, v19
	v_mul_f32_e32 v22, v18, v22
	v_mul_f32_e32 v23, v19, v23
	v_fma_f32 v22, v18, v22, v18
	v_fma_f32 v23, v19, v23, v19
	v_mul_f32_e32 v22, 0x3f4c422a, v22
	v_mul_f32_e32 v23, 0x3f4c422a, v23
	v_mul_f32_e32 v22, -2.0, v22
	v_mul_f32_e32 v23, -2.0, v23
	v_mul_f32_e32 v22, 0x3fb8aa3b, v22
	v_mul_f32_e32 v23, 0x3fb8aa3b, v23
	v_exp_f32_e32 v22, v22
	v_exp_f32_e32 v23, v23
	s_nop 0
	v_pk_add_f32 v[22:23], v[22:23], 1.0 op_sel_hi:[1,0]
	s_nop 0
	v_div_scale_f32 v24, s[4:5], v23, v23, v19
	v_rcp_f32_e32 v25, v24
	s_nop 0
	v_fma_f32 v26, -v24, v25, 1.0
	v_fmac_f32_e32 v25, v26, v25
	v_div_scale_f32 v26, vcc, v19, v23, v19
	v_mul_f32_e32 v27, v26, v25
	v_fma_f32 v28, -v24, v27, v26
	v_fmac_f32_e32 v27, v28, v25
	v_fma_f32 v24, -v24, v27, v26
	v_div_fmas_f32 v24, v24, v25, v27
	v_div_fixup_f32 v19, v24, v23, v19
	v_div_scale_f32 v23, s[4:5], v22, v22, v18
	v_rcp_f32_e32 v24, v23
	s_nop 0
	v_fma_f32 v25, -v23, v24, 1.0
	v_fmac_f32_e32 v24, v25, v24
	v_div_scale_f32 v25, vcc, v18, v22, v18
	v_mul_f32_e32 v26, v25, v24
	v_fma_f32 v27, -v23, v26, v25
	v_fmac_f32_e32 v26, v27, v24
	v_fma_f32 v23, -v23, v26, v25
	v_div_fmas_f32 v23, v23, v24, v26
	v_div_fixup_f32 v18, v23, v22, v18
	v_cvt_pk_bf16_f32 v18, v18, v19
	v_mul_f32_e32 v19, 0x3d372713, v20
	v_mul_f32_e32 v19, v20, v19
	v_fma_f32 v19, v20, v19, v20
	v_mul_f32_e32 v19, 0x3f4c422a, v19
	v_mul_f32_e32 v19, -2.0, v19
	v_mul_f32_e32 v19, 0x3fb8aa3b, v19
	v_exp_f32_e32 v22, v19
	v_mul_f32_e32 v19, 0x3d372713, v21
	v_mul_f32_e32 v19, v21, v19
	v_fma_f32 v19, v21, v19, v21
	v_mul_f32_e32 v19, 0x3f4c422a, v19
	v_mul_f32_e32 v19, -2.0, v19
	v_mul_f32_e32 v19, 0x3fb8aa3b, v19
	v_exp_f32_e32 v23, v19
	s_nop 0
	v_pk_add_f32 v[22:23], v[22:23], 1.0 op_sel_hi:[1,0]
	s_nop 0
	v_div_scale_f32 v19, s[4:5], v23, v23, v21
	v_rcp_f32_e32 v24, v19
	s_nop 0
	v_fma_f32 v25, -v19, v24, 1.0
	v_fmac_f32_e32 v24, v25, v24
	v_div_scale_f32 v25, vcc, v21, v23, v21
	v_mul_f32_e32 v26, v25, v24
	v_fma_f32 v27, -v19, v26, v25
	v_fmac_f32_e32 v26, v27, v24
	v_fma_f32 v19, -v19, v26, v25
	v_div_fmas_f32 v19, v19, v24, v26
	v_div_fixup_f32 v19, v19, v23, v21
	v_div_scale_f32 v21, s[4:5], v22, v22, v20
	v_rcp_f32_e32 v23, v21
	s_nop 0
	v_fma_f32 v24, -v21, v23, 1.0
	v_fmac_f32_e32 v23, v24, v23
	v_div_scale_f32 v24, vcc, v20, v22, v20
	v_mul_f32_e32 v25, v24, v23
	v_fma_f32 v26, -v21, v25, v24
	v_fmac_f32_e32 v25, v26, v23
	v_fma_f32 v21, -v21, v25, v24
	v_div_fmas_f32 v21, v21, v23, v25
	v_div_fixup_f32 v20, v21, v22, v20
	v_cvt_pk_bf16_f32 v19, v20, v19
	v_lshl_add_u64 v[20:21], v[34:35], 0, v[50:51]
	v_lshlrev_b64 v[20:21], 5, v[20:21]
	v_lshl_add_u64 v[20:21], v[66:67], 0, v[20:21]
	global_store_dwordx2 v[20:21], v[18:19], off
	v_or_b32_e32 v18, 3, v1
	v_mul_f32_e32 v1, 0x3d372713, v14
	v_mul_f32_e32 v1, v14, v1
	v_fma_f32 v1, v14, v1, v14
	v_mul_f32_e32 v1, 0x3f4c422a, v1
	v_mul_f32_e32 v1, -2.0, v1
	v_mul_f32_e32 v1, 0x3fb8aa3b, v1
	v_exp_f32_e32 v20, v1
	v_mul_f32_e32 v1, 0x3d372713, v15
	v_mul_f32_e32 v1, v15, v1
	v_fma_f32 v1, v15, v1, v15
	v_mul_f32_e32 v1, 0x3f4c422a, v1
	v_mul_f32_e32 v1, -2.0, v1
	v_mul_f32_e32 v1, 0x3fb8aa3b, v1
	v_exp_f32_e32 v21, v1
	v_ashrrev_i32_e32 v19, 31, v18
	v_lshl_add_u64 v[18:19], s[2:3], 0, v[18:19]
	v_pk_add_f32 v[20:21], v[20:21], 1.0 op_sel_hi:[1,0]
	s_nop 0
	v_div_scale_f32 v1, s[2:3], v21, v21, v15
	v_rcp_f32_e32 v22, v1
	s_nop 0
	v_fma_f32 v23, -v1, v22, 1.0
	v_fmac_f32_e32 v22, v23, v22
	v_div_scale_f32 v23, vcc, v15, v21, v15
	v_mul_f32_e32 v24, v23, v22
	v_fma_f32 v25, -v1, v24, v23
	v_fmac_f32_e32 v24, v25, v22
	v_fma_f32 v1, -v1, v24, v23
	v_div_fmas_f32 v1, v1, v22, v24
	v_div_fixup_f32 v1, v1, v21, v15
	v_div_scale_f32 v15, s[2:3], v20, v20, v14
	v_rcp_f32_e32 v21, v15
	s_nop 0
	v_fma_f32 v22, -v15, v21, 1.0
	v_fmac_f32_e32 v21, v22, v21
	v_div_scale_f32 v22, vcc, v14, v20, v14
	v_mul_f32_e32 v23, v22, v21
	v_fma_f32 v24, -v15, v23, v22
	v_fmac_f32_e32 v23, v24, v21
	v_fma_f32 v15, -v15, v23, v22
	v_div_fmas_f32 v15, v15, v21, v23
	v_div_fixup_f32 v14, v15, v20, v14
	v_cvt_pk_bf16_f32 v14, v14, v1
	v_mul_f32_e32 v1, 0x3d372713, v16
	v_mul_f32_e32 v1, v16, v1
	v_fma_f32 v1, v16, v1, v16
	v_mul_f32_e32 v1, 0x3f4c422a, v1
	v_mul_f32_e32 v1, -2.0, v1
	v_mul_f32_e32 v1, 0x3fb8aa3b, v1
	v_exp_f32_e32 v20, v1
	v_mul_f32_e32 v1, 0x3d372713, v17
	v_mul_f32_e32 v1, v17, v1
	v_fma_f32 v1, v17, v1, v17
	v_mul_f32_e32 v1, 0x3f4c422a, v1
	v_mul_f32_e32 v1, -2.0, v1
	v_mul_f32_e32 v1, 0x3fb8aa3b, v1
	v_exp_f32_e32 v21, v1
	s_nop 0
	v_pk_add_f32 v[20:21], v[20:21], 1.0 op_sel_hi:[1,0]
	s_nop 0
	v_div_scale_f32 v1, s[2:3], v21, v21, v17
	v_rcp_f32_e32 v15, v1
	s_nop 0
	v_fma_f32 v22, -v1, v15, 1.0
	v_fmac_f32_e32 v15, v22, v15
	v_div_scale_f32 v22, vcc, v17, v21, v17
	v_mul_f32_e32 v23, v22, v15
	v_fma_f32 v24, -v1, v23, v22
	v_fmac_f32_e32 v23, v24, v15
	v_fma_f32 v1, -v1, v23, v22
	v_div_fmas_f32 v1, v1, v15, v23
	v_div_scale_f32 v15, s[2:3], v20, v20, v16
	v_div_fixup_f32 v1, v1, v21, v17
	v_rcp_f32_e32 v17, v15
	s_nop 0
	v_fma_f32 v21, -v15, v17, 1.0
	v_fmac_f32_e32 v17, v21, v17
	v_div_scale_f32 v21, vcc, v16, v20, v16
	v_mul_f32_e32 v22, v21, v17
	v_fma_f32 v23, -v15, v22, v21
	v_fmac_f32_e32 v22, v23, v17
	v_fma_f32 v15, -v15, v22, v21
	v_div_fmas_f32 v15, v15, v17, v22
	v_div_fixup_f32 v15, v15, v20, v16
	v_cvt_pk_bf16_f32 v15, v15, v1
	v_mul_f32_e32 v1, 0x3d372713, v10
	v_mul_f32_e32 v1, v10, v1
	v_fma_f32 v1, v10, v1, v10
	v_lshl_add_u64 v[16:17], v[18:19], 0, v[130:131]
	v_mul_f32_e32 v1, 0x3f4c422a, v1
	v_lshlrev_b64 v[16:17], 5, v[16:17]
	v_mul_f32_e32 v1, -2.0, v1
	v_lshl_add_u64 v[16:17], v[66:67], 0, v[16:17]
	v_mul_f32_e32 v1, 0x3fb8aa3b, v1
	global_store_dwordx2 v[16:17], v[14:15], off
	v_exp_f32_e32 v14, v1
	v_mul_f32_e32 v1, 0x3d372713, v11
	v_mul_f32_e32 v1, v11, v1
	v_fma_f32 v1, v11, v1, v11
	v_mul_f32_e32 v1, 0x3f4c422a, v1
	v_mul_f32_e32 v1, -2.0, v1
	v_mul_f32_e32 v1, 0x3fb8aa3b, v1
	v_exp_f32_e32 v15, v1
	s_nop 0
	v_pk_add_f32 v[14:15], v[14:15], 1.0 op_sel_hi:[1,0]
	s_nop 0
	v_div_scale_f32 v1, s[2:3], v15, v15, v11
	v_rcp_f32_e32 v16, v1
	s_nop 0
	v_fma_f32 v17, -v1, v16, 1.0
	v_fmac_f32_e32 v16, v17, v16
	v_div_scale_f32 v17, vcc, v11, v15, v11
	v_mul_f32_e32 v20, v17, v16
	v_fma_f32 v21, -v1, v20, v17
	v_fmac_f32_e32 v20, v21, v16
	v_fma_f32 v1, -v1, v20, v17
	v_div_fmas_f32 v1, v1, v16, v20
	v_div_fixup_f32 v1, v1, v15, v11
	v_div_scale_f32 v11, s[2:3], v14, v14, v10
	v_rcp_f32_e32 v15, v11
	s_nop 0
	v_fma_f32 v16, -v11, v15, 1.0
	v_fmac_f32_e32 v15, v16, v15
	v_div_scale_f32 v16, vcc, v10, v14, v10
	v_mul_f32_e32 v17, v16, v15
	v_fma_f32 v20, -v11, v17, v16
	v_fmac_f32_e32 v17, v20, v15
	v_fma_f32 v11, -v11, v17, v16
	v_div_fmas_f32 v11, v11, v15, v17
	v_div_fixup_f32 v10, v11, v14, v10
	v_cvt_pk_bf16_f32 v10, v10, v1
	v_mul_f32_e32 v1, 0x3d372713, v12
	v_mul_f32_e32 v1, v12, v1
	v_fma_f32 v1, v12, v1, v12
	v_mul_f32_e32 v1, 0x3f4c422a, v1
	v_mul_f32_e32 v1, -2.0, v1
	v_mul_f32_e32 v1, 0x3fb8aa3b, v1
	v_exp_f32_e32 v14, v1
	v_mul_f32_e32 v1, 0x3d372713, v13
	v_mul_f32_e32 v1, v13, v1
	v_fma_f32 v1, v13, v1, v13
	v_mul_f32_e32 v1, 0x3f4c422a, v1
	v_mul_f32_e32 v1, -2.0, v1
	v_mul_f32_e32 v1, 0x3fb8aa3b, v1
	v_exp_f32_e32 v15, v1
	s_nop 0
	v_pk_add_f32 v[14:15], v[14:15], 1.0 op_sel_hi:[1,0]
	s_nop 0
	v_div_scale_f32 v1, s[2:3], v15, v15, v13
	v_rcp_f32_e32 v11, v1
	s_nop 0
	v_fma_f32 v16, -v1, v11, 1.0
	v_fmac_f32_e32 v11, v16, v11
	v_div_scale_f32 v16, vcc, v13, v15, v13
	v_mul_f32_e32 v17, v16, v11
	v_fma_f32 v20, -v1, v17, v16
	v_fmac_f32_e32 v17, v20, v11
	v_fma_f32 v1, -v1, v17, v16
	v_div_fmas_f32 v1, v1, v11, v17
	v_div_scale_f32 v11, s[2:3], v14, v14, v12
	v_div_fixup_f32 v1, v1, v15, v13
	v_rcp_f32_e32 v13, v11
	s_nop 0
	v_fma_f32 v15, -v11, v13, 1.0
	v_fmac_f32_e32 v13, v15, v13
	v_div_scale_f32 v15, vcc, v12, v14, v12
	v_mul_f32_e32 v16, v15, v13
	v_fma_f32 v17, -v11, v16, v15
	v_fmac_f32_e32 v16, v17, v13
	v_fma_f32 v11, -v11, v16, v15
	v_div_fmas_f32 v11, v11, v13, v16
	v_div_fixup_f32 v11, v11, v14, v12
	v_cvt_pk_bf16_f32 v11, v11, v1
	v_mul_f32_e32 v1, 0x3d372713, v6
	v_mul_f32_e32 v1, v6, v1
	v_fma_f32 v1, v6, v1, v6
	v_lshl_add_u64 v[12:13], v[18:19], 0, v[58:59]
	v_mul_f32_e32 v1, 0x3f4c422a, v1
	v_lshlrev_b64 v[12:13], 5, v[12:13]
	v_mul_f32_e32 v1, -2.0, v1
	v_lshl_add_u64 v[12:13], v[66:67], 0, v[12:13]
	v_mul_f32_e32 v1, 0x3fb8aa3b, v1
	global_store_dwordx2 v[12:13], v[10:11], off
	v_exp_f32_e32 v10, v1
	v_mul_f32_e32 v1, 0x3d372713, v7
	v_mul_f32_e32 v1, v7, v1
	v_fma_f32 v1, v7, v1, v7
	v_mul_f32_e32 v1, 0x3f4c422a, v1
	v_mul_f32_e32 v1, -2.0, v1
	v_mul_f32_e32 v1, 0x3fb8aa3b, v1
	v_exp_f32_e32 v11, v1
	s_nop 0
	v_pk_add_f32 v[10:11], v[10:11], 1.0 op_sel_hi:[1,0]
	s_nop 0
	v_div_scale_f32 v1, s[2:3], v11, v11, v7
	v_rcp_f32_e32 v12, v1
	s_nop 0
	v_fma_f32 v13, -v1, v12, 1.0
	v_fmac_f32_e32 v12, v13, v12
	v_div_scale_f32 v13, vcc, v7, v11, v7
	v_mul_f32_e32 v14, v13, v12
	v_fma_f32 v15, -v1, v14, v13
	v_fmac_f32_e32 v14, v15, v12
	v_fma_f32 v1, -v1, v14, v13
	v_div_fmas_f32 v1, v1, v12, v14
	v_div_fixup_f32 v1, v1, v11, v7
	v_div_scale_f32 v7, s[2:3], v10, v10, v6
	v_rcp_f32_e32 v11, v7
	s_nop 0
	v_fma_f32 v12, -v7, v11, 1.0
	v_fmac_f32_e32 v11, v12, v11
	v_div_scale_f32 v12, vcc, v6, v10, v6
	v_mul_f32_e32 v13, v12, v11
	v_fma_f32 v14, -v7, v13, v12
	v_fmac_f32_e32 v13, v14, v11
	v_fma_f32 v7, -v7, v13, v12
	v_div_fmas_f32 v7, v7, v11, v13
	v_div_fixup_f32 v6, v7, v10, v6
	v_cvt_pk_bf16_f32 v6, v6, v1
	v_mul_f32_e32 v1, 0x3d372713, v8
	v_mul_f32_e32 v1, v8, v1
	v_fma_f32 v1, v8, v1, v8
	v_mul_f32_e32 v1, 0x3f4c422a, v1
	v_mul_f32_e32 v1, -2.0, v1
	v_mul_f32_e32 v1, 0x3fb8aa3b, v1
	v_exp_f32_e32 v10, v1
	v_mul_f32_e32 v1, 0x3d372713, v9
	v_mul_f32_e32 v1, v9, v1
	v_fma_f32 v1, v9, v1, v9
	v_mul_f32_e32 v1, 0x3f4c422a, v1
	v_mul_f32_e32 v1, -2.0, v1
	v_mul_f32_e32 v1, 0x3fb8aa3b, v1
	v_exp_f32_e32 v11, v1
	s_nop 0
	v_pk_add_f32 v[10:11], v[10:11], 1.0 op_sel_hi:[1,0]
	s_nop 0
	v_div_scale_f32 v1, s[2:3], v11, v11, v9
	v_rcp_f32_e32 v7, v1
	s_nop 0
	v_fma_f32 v12, -v1, v7, 1.0
	v_fmac_f32_e32 v7, v12, v7
	v_div_scale_f32 v12, vcc, v9, v11, v9
	v_mul_f32_e32 v13, v12, v7
	v_fma_f32 v14, -v1, v13, v12
	v_fmac_f32_e32 v13, v14, v7
	v_fma_f32 v1, -v1, v13, v12
	v_div_fmas_f32 v1, v1, v7, v13
	v_div_scale_f32 v7, s[2:3], v10, v10, v8
	v_div_fixup_f32 v1, v1, v11, v9
	v_rcp_f32_e32 v9, v7
	s_nop 0
	v_fma_f32 v11, -v7, v9, 1.0
	v_fmac_f32_e32 v9, v11, v9
	v_div_scale_f32 v11, vcc, v8, v10, v8
	v_mul_f32_e32 v12, v11, v9
	v_fma_f32 v13, -v7, v12, v11
	v_fmac_f32_e32 v12, v13, v9
	v_fma_f32 v7, -v7, v12, v11
	v_div_fmas_f32 v7, v7, v9, v12
	v_div_fixup_f32 v7, v7, v10, v8
	v_cvt_pk_bf16_f32 v7, v7, v1
	v_mul_f32_e32 v1, 0x3d372713, v2
	v_mul_f32_e32 v1, v2, v1
	v_fma_f32 v1, v2, v1, v2
	v_lshl_add_u64 v[8:9], v[18:19], 0, v[54:55]
	v_mul_f32_e32 v1, 0x3f4c422a, v1
	v_lshlrev_b64 v[8:9], 5, v[8:9]
	v_mul_f32_e32 v1, -2.0, v1
	v_lshl_add_u64 v[8:9], v[66:67], 0, v[8:9]
	v_mul_f32_e32 v1, 0x3fb8aa3b, v1
	global_store_dwordx2 v[8:9], v[6:7], off
	v_exp_f32_e32 v6, v1
	v_mul_f32_e32 v1, 0x3d372713, v3
	v_mul_f32_e32 v1, v3, v1
	v_fma_f32 v1, v3, v1, v3
	v_mul_f32_e32 v1, 0x3f4c422a, v1
	v_mul_f32_e32 v1, -2.0, v1
	v_mul_f32_e32 v1, 0x3fb8aa3b, v1
	v_exp_f32_e32 v7, v1
	s_nop 0
	v_pk_add_f32 v[6:7], v[6:7], 1.0 op_sel_hi:[1,0]
	s_nop 0
	v_div_scale_f32 v1, s[2:3], v7, v7, v3
	v_rcp_f32_e32 v8, v1
	s_nop 0
	v_fma_f32 v9, -v1, v8, 1.0
	v_fmac_f32_e32 v8, v9, v8
	v_div_scale_f32 v9, vcc, v3, v7, v3
	v_mul_f32_e32 v10, v9, v8
	v_fma_f32 v11, -v1, v10, v9
	v_fmac_f32_e32 v10, v11, v8
	v_fma_f32 v1, -v1, v10, v9
	v_div_fmas_f32 v1, v1, v8, v10
	v_div_fixup_f32 v1, v1, v7, v3
	v_div_scale_f32 v3, s[2:3], v6, v6, v2
	v_rcp_f32_e32 v7, v3
	s_nop 0
	v_fma_f32 v8, -v3, v7, 1.0
	v_fmac_f32_e32 v7, v8, v7
	v_div_scale_f32 v8, vcc, v2, v6, v2
	v_mul_f32_e32 v9, v8, v7
	v_fma_f32 v10, -v3, v9, v8
	v_fmac_f32_e32 v9, v10, v7
	v_fma_f32 v3, -v3, v9, v8
	v_div_fmas_f32 v3, v3, v7, v9
	v_div_fixup_f32 v2, v3, v6, v2
	v_cvt_pk_bf16_f32 v2, v2, v1
	v_mul_f32_e32 v1, 0x3d372713, v4
	v_mul_f32_e32 v1, v4, v1
	v_fma_f32 v1, v4, v1, v4
	v_mul_f32_e32 v1, 0x3f4c422a, v1
	v_mul_f32_e32 v1, -2.0, v1
	v_mul_f32_e32 v1, 0x3fb8aa3b, v1
	v_exp_f32_e32 v6, v1
	v_mul_f32_e32 v1, 0x3d372713, v5
	v_mul_f32_e32 v1, v5, v1
	v_fma_f32 v1, v5, v1, v5
	v_mul_f32_e32 v1, 0x3f4c422a, v1
	v_mul_f32_e32 v1, -2.0, v1
	v_mul_f32_e32 v1, 0x3fb8aa3b, v1
	v_exp_f32_e32 v7, v1
	s_nop 0
	v_pk_add_f32 v[6:7], v[6:7], 1.0 op_sel_hi:[1,0]
	s_nop 0
	v_div_scale_f32 v1, s[2:3], v7, v7, v5
	v_rcp_f32_e32 v3, v1
	s_nop 0
	v_fma_f32 v8, -v1, v3, 1.0
	v_fmac_f32_e32 v3, v8, v3
	v_div_scale_f32 v8, vcc, v5, v7, v5
	v_mul_f32_e32 v9, v8, v3
	v_fma_f32 v10, -v1, v9, v8
	v_fmac_f32_e32 v9, v10, v3
	v_fma_f32 v1, -v1, v9, v8
	v_div_fmas_f32 v1, v1, v3, v9
	v_div_scale_f32 v3, s[2:3], v6, v6, v4
	v_div_fixup_f32 v1, v1, v7, v5
	v_rcp_f32_e32 v5, v3
	s_nop 0
	v_fma_f32 v7, -v3, v5, 1.0
	v_fmac_f32_e32 v5, v7, v5
	v_div_scale_f32 v7, vcc, v4, v6, v4
	v_mul_f32_e32 v8, v7, v5
	v_fma_f32 v9, -v3, v8, v7
	v_fmac_f32_e32 v8, v9, v5
	v_fma_f32 v3, -v3, v8, v7
	v_div_fmas_f32 v3, v3, v5, v8
	v_div_fixup_f32 v3, v3, v6, v4
	v_lshl_add_u64 v[4:5], v[18:19], 0, v[50:51]
	v_lshlrev_b64 v[4:5], 5, v[4:5]
	v_cvt_pk_bf16_f32 v3, v3, v1
	v_lshl_add_u64 v[4:5], v[66:67], 0, v[4:5]
	global_store_dwordx2 v[4:5], v[2:3], off
	s_barrier

.LBB0_537:
	v_lshl_add_u64 v[140:141], v[74:75], 0, s[2:3]
	v_add_co_u32_e32 v130, vcc, s5, v140
	v_lshl_add_u64 v[142:143], v[76:77], 0, s[2:3]
	s_nop 0
	v_addc_co_u32_e32 v134, vcc, 0, v141, vcc
	v_add_co_u32_e32 v137, vcc, s5, v142
	v_lshl_add_u64 v[140:141], v[78:79], 0, s[2:3]
	s_nop 0
	v_addc_co_u32_e32 v144, vcc, 0, v143, vcc
	v_add_co_u32_e32 v142, vcc, s5, v140
	v_lshl_add_u64 v[146:147], v[80:81], 0, s[2:3]
	s_nop 0
	v_addc_co_u32_e32 v143, vcc, 0, v141, vcc
	v_add_co_u32_e32 v140, vcc, s5, v146
	s_nop 0
	s_nop 0
	v_addc_co_u32_e32 v141, vcc, 0, v147, vcc
	s_nop 0
	s_nop 0
	s_nop 0
	s_nop 0
	s_nop 0
	s_nop 0
	s_nop 0
	s_nop 0
	s_nop 0
	s_nop 0
	s_nop 0
	s_nop 0
	s_nop 0
	s_nop 1
	s_nop 0
	v_mov_b32_e32 v154, v130
	v_mov_b32_e32 v155, v134
	global_load_dwordx4 v[156:159], v[154:155], off offset:320
	v_mov_b32_e32 v154, v137
	v_mov_b32_e32 v155, v144
	global_load_dwordx4 v[162:165], v[154:155], off offset:320
	global_load_dwordx4 v[168:171], v[142:143], off offset:320
	global_load_dwordx4 v[174:177], v[140:141], off offset:320
	s_nop 0
	s_nop 0
	ds_read_b128 v[180:183], v228 offset:64
	ds_read_b128 v[140:143], v228 offset:8512
	ds_read_b128 v[184:187], v228 offset:16960
	s_nop 0
	s_nop 0
	ds_read_b128 v[146:149], v228 offset:25408
	v_lshl_add_u64 v[82:83], v[74:75], 0, s[2:3]
	v_add_co_u32_e32 v82, vcc, s5, v82
	v_lshl_add_u64 v[90:91], v[76:77], 0, s[2:3]
	s_nop 0
	v_addc_co_u32_e32 v83, vcc, 0, v83, vcc
	v_add_co_u32_e32 v118, vcc, s5, v90
	v_lshl_add_u64 v[94:95], v[78:79], 0, s[2:3]
	s_nop 0
	v_addc_co_u32_e32 v119, vcc, 0, v91, vcc
	v_add_co_u32_e32 v120, vcc, s5, v94
	v_lshl_add_u64 v[98:99], v[80:81], 0, s[2:3]
	s_nop 0
	v_addc_co_u32_e32 v121, vcc, 0, v95, vcc
	v_add_co_u32_e32 v122, vcc, s5, v98
	s_nop 0
	s_nop 0
	v_addc_co_u32_e32 v123, vcc, 0, v99, vcc
	s_nop 0
	s_nop 0
	s_nop 0
	s_nop 0
	s_nop 0
	s_nop 0
	s_nop 0
	s_nop 0
	global_load_dwordx4 v[86:89], v[82:83], off offset:256
	global_load_dwordx4 v[90:93], v[118:119], off offset:256
	global_load_dwordx4 v[94:97], v[120:121], off offset:256
	global_load_dwordx4 v[98:101], v[122:123], off offset:256
	s_nop 0
	s_nop 0
	s_nop 0
	s_nop 0
	s_nop 0
	ds_read_b128 v[102:105], v228
	ds_read_b128 v[106:109], v228 offset:8448
	s_nop 0
	ds_read_b128 v[110:113], v228 offset:16896
	ds_read_b128 v[114:117], v228 offset:25344
	s_add_u32 s2, s2, 0x80
	s_addc_u32 s3, s3, 0
	s_cmpk_lg_i32 s2, 0x200
	s_waitcnt vmcnt(0) lgkmcnt(0)
	v_mfma_f32_16x16x32_bf16 v[62:65], v[86:89], v[102:105], v[62:65]
	s_waitcnt vmcnt(2)
	v_mfma_f32_16x16x32_bf16 v[58:61], v[86:89], v[106:109], v[58:61]
	s_waitcnt vmcnt(1)
	v_mfma_f32_16x16x32_bf16 v[54:57], v[86:89], v[110:113], v[54:57]
	s_waitcnt vmcnt(0)
	v_mfma_f32_16x16x32_bf16 v[50:53], v[86:89], v[114:117], v[50:53]
	v_mfma_f32_16x16x32_bf16 v[38:41], v[90:93], v[102:105], v[38:41]
	v_mfma_f32_16x16x32_bf16 v[10:13], v[90:93], v[106:109], v[10:13]
	v_mfma_f32_16x16x32_bf16 v[6:9], v[90:93], v[110:113], v[6:9]
	v_mfma_f32_16x16x32_bf16 v[2:5], v[90:93], v[114:117], v[2:5]
	v_mfma_f32_16x16x32_bf16 v[46:49], v[94:97], v[102:105], v[46:49]
	v_mfma_f32_16x16x32_bf16 v[42:45], v[94:97], v[106:109], v[42:45]
	v_mfma_f32_16x16x32_bf16 v[34:37], v[94:97], v[110:113], v[34:37]
	v_mfma_f32_16x16x32_bf16 v[26:29], v[94:97], v[114:117], v[26:29]
	v_mfma_f32_16x16x32_bf16 v[30:33], v[98:101], v[102:105], v[30:33]
	v_mfma_f32_16x16x32_bf16 v[22:25], v[98:101], v[106:109], v[22:25]
	v_mfma_f32_16x16x32_bf16 v[18:21], v[98:101], v[110:113], v[18:21]
	v_mfma_f32_16x16x32_bf16 v[14:17], v[98:101], v[114:117], v[14:17]
	s_waitcnt vmcnt(0)
	v_mfma_f32_16x16x32_bf16 v[62:65], v[156:159], v[180:183], v[62:65]
	v_mfma_f32_16x16x32_bf16 v[58:61], v[156:159], v[140:143], v[58:61]
	v_mfma_f32_16x16x32_bf16 v[54:57], v[156:159], v[184:187], v[54:57]
	v_mfma_f32_16x16x32_bf16 v[50:53], v[156:159], v[146:149], v[50:53]
	v_mfma_f32_16x16x32_bf16 v[38:41], v[162:165], v[180:183], v[38:41]
	v_mfma_f32_16x16x32_bf16 v[10:13], v[162:165], v[140:143], v[10:13]
	v_mfma_f32_16x16x32_bf16 v[6:9], v[162:165], v[184:187], v[6:9]
	v_mfma_f32_16x16x32_bf16 v[2:5], v[162:165], v[146:149], v[2:5]
	v_mfma_f32_16x16x32_bf16 v[46:49], v[168:171], v[180:183], v[46:49]
	v_mfma_f32_16x16x32_bf16 v[42:45], v[168:171], v[140:143], v[42:45]
	v_mfma_f32_16x16x32_bf16 v[34:37], v[168:171], v[184:187], v[34:37]
	v_mfma_f32_16x16x32_bf16 v[26:29], v[168:171], v[146:149], v[26:29]
	v_mfma_f32_16x16x32_bf16 v[30:33], v[174:177], v[180:183], v[30:33]
	v_mfma_f32_16x16x32_bf16 v[22:25], v[174:177], v[140:143], v[22:25]
	v_mfma_f32_16x16x32_bf16 v[18:21], v[174:177], v[184:187], v[18:21]
	v_mfma_f32_16x16x32_bf16 v[14:17], v[174:177], v[146:149], v[14:17]
	v_add_u32_e32 v228, 0x80, v228
	s_cbranch_scc1 .LBB0_537
	v_and_b32_e32 v66, 3, v84
	v_and_b32_e32 v1, 0xffffffc0, v1
	s_lshl_b64 s[0:1], s[0:1], 9
	v_readlane_b32 s2, v254, 9
	v_lshl_or_b32 v66, v66, 2, v1
	v_lshl_or_b32 v68, s4, 6, v85
	v_readlane_b32 s3, v254, 10
	s_add_u32 s0, s2, s0
	s_addc_u32 s1, s3, s1
	v_ashrrev_i32_e32 v67, 31, v66
	v_ashrrev_i32_e32 v69, 31, v68
	v_lshl_add_u64 v[66:67], v[66:67], 1, s[0:1]
	v_cvt_pk_bf16_f32 v62, v62, v63
	v_cvt_pk_bf16_f32 v63, v64, v65
	v_lshlrev_b64 v[64:65], 14, v[68:69]
	v_lshl_add_u64 v[64:65], v[66:67], 0, v[64:65]
	global_store_dwordx2 v[64:65], v[62:63], off
	v_or_b32_e32 v62, 16, v68
	v_ashrrev_i32_e32 v63, 31, v62
	v_cvt_pk_bf16_f32 v58, v58, v59
	v_cvt_pk_bf16_f32 v59, v60, v61
	v_lshlrev_b64 v[60:61], 14, v[62:63]
	v_lshl_add_u64 v[60:61], v[66:67], 0, v[60:61]
	global_store_dwordx2 v[60:61], v[58:59], off
	v_or_b32_e32 v58, 32, v68
	v_ashrrev_i32_e32 v59, 31, v58
	v_cvt_pk_bf16_f32 v54, v54, v55
	v_cvt_pk_bf16_f32 v55, v56, v57
	v_lshlrev_b64 v[56:57], 14, v[58:59]
	v_lshl_add_u64 v[56:57], v[66:67], 0, v[56:57]
	global_store_dwordx2 v[56:57], v[54:55], off
	v_or_b32_e32 v54, 48, v68
	v_ashrrev_i32_e32 v55, 31, v54
	v_cvt_pk_bf16_f32 v50, v50, v51
	v_cvt_pk_bf16_f32 v51, v52, v53
	v_lshlrev_b64 v[52:53], 14, v[54:55]
	v_lshl_add_u64 v[52:53], v[66:67], 0, v[52:53]
	v_cvt_pk_bf16_f32 v2, v2, v3
	v_cvt_pk_bf16_f32 v3, v4, v5
	global_store_dwordx2 v[52:53], v[2:3], off offset:32
	v_cvt_pk_bf16_f32 v2, v46, v47
	v_cvt_pk_bf16_f32 v3, v48, v49
	global_store_dwordx2 v[64:65], v[2:3], off offset:64
	v_cvt_pk_bf16_f32 v2, v42, v43
	v_cvt_pk_bf16_f32 v3, v44, v45
	global_store_dwordx2 v[60:61], v[2:3], off offset:64
	v_cvt_pk_bf16_f32 v2, v34, v35
	v_cvt_pk_bf16_f32 v3, v36, v37
	global_store_dwordx2 v[56:57], v[2:3], off offset:64
	v_cvt_pk_bf16_f32 v2, v26, v27
	v_cvt_pk_bf16_f32 v3, v28, v29
	global_store_dwordx2 v[52:53], v[2:3], off offset:64
	v_cvt_pk_bf16_f32 v2, v30, v31
	v_cvt_pk_bf16_f32 v3, v32, v33
	global_store_dwordx2 v[64:65], v[2:3], off offset:96
	v_cvt_pk_bf16_f32 v2, v22, v23
	v_cvt_pk_bf16_f32 v3, v24, v25
	global_store_dwordx2 v[60:61], v[2:3], off offset:96
	v_cvt_pk_bf16_f32 v2, v18, v19
	v_cvt_pk_bf16_f32 v3, v20, v21
	v_cvt_pk_bf16_f32 v38, v38, v39
	v_cvt_pk_bf16_f32 v39, v40, v41
	v_cvt_pk_bf16_f32 v10, v10, v11
	v_cvt_pk_bf16_f32 v11, v12, v13
	v_cvt_pk_bf16_f32 v6, v6, v7
	v_cvt_pk_bf16_f32 v7, v8, v9
	global_store_dwordx2 v[56:57], v[2:3], off offset:96
	v_cvt_pk_bf16_f32 v2, v14, v15
	v_cvt_pk_bf16_f32 v3, v16, v17
	global_store_dwordx2 v[52:53], v[50:51], off
	global_store_dwordx2 v[64:65], v[38:39], off offset:32
	global_store_dwordx2 v[60:61], v[10:11], off offset:32
	global_store_dwordx2 v[56:57], v[6:7], off offset:32
	global_store_dwordx2 v[52:53], v[2:3], off offset:96
